# baseline (speedup 1.0000x reference)
; __device__ __forceinline__ void unpack8(u32x4 v, float* f) { f[0] = bflo(v[0]); f[1] = bfhi(v[0]); f[2] = bflo(v[1]); f[3] = bfhi(v[1]); f[4] = bflo(v[2]); f[5] = bfhi(v[2]); f[6] = bflo(v[3]); f[7] = bfhi(v[3]); }
; __device__ __forceinline__ void dn_prep_unit(int layer, int sample, int b, int n, int h, unsigned char* shm) {
;     ...
;     {
;         const int tt = tid >> 3, part = tid & 7; const float gc = gcum[tt], bt = beta[tt], glast = gcum[63];
;         const float eg = expf(gc), ekd = expf(glast - gc);
; #pragma unroll
;         for (int sel = 0; sel < 3; ++sel) {
;             const int ch = sel * 1024 + h * 128 + part * 16; float y[16];
; #pragma unroll
;             for (int i = 0; i < 16; ++i) y[i] = 0.f;
;             if (tt < rows) {
; #pragma unroll
;                 for (int j = 0; j < 4; ++j) { const int lt = n * 64 + tt - 3 + j; float x[16];
;                     if (lt >= 0) { const bf16_t* s = P + (tokb + lt) * NINP + C_DQ + ch; unpack8(*(const u32x4*)s, x); unpack8(*(const u32x4*)(s + 8), x + 8); }
.LBB0_956:
	s_or_b64 exec, exec, s[20:21]
	v_ashrrev_i32_e32 v135, 3, v146
	v_lshl_add_u32 v3, v135, 2, 0
	s_waitcnt lgkmcnt(0)
	s_barrier
	ds_read2st64_b32 v[122:123], v3 offset1:1
	ds_read_b32 v136, v0 offset:252
	v_lshlrev_b32_e32 v3, 4, v146
	v_and_b32_e32 v134, 0x70, v3
	v_cmp_lt_i32_e64 s[4:5], v135, v2
	v_readlane_b32 s20, v254, 18
	v_lshl_add_u64 v[2:3], s[30:31], 0, v[116:117]
	v_lshl_add_u32 v124, v1, 6, v135
	v_lshl_add_u32 v129, v134, 2, s20
	v_mad_u64_u32 v[120:121], s[20:21], v2, 3, 0
	v_add_u32_e32 v126, -3, v124
	v_mad_i32_i24 v121, v3, 3, v121
	v_mov_b32_e32 v19, 0
	v_mov_b32_e32 v18, 0
	v_mov_b32_e32 v17, 0
	v_mov_b32_e32 v16, 0
	v_mov_b32_e32 v15, 0
	v_mov_b32_e32 v14, 0
	v_mov_b32_e32 v13, 0
	v_mov_b32_e32 v12, 0
	v_mov_b32_e32 v11, 0
	v_mov_b32_e32 v10, 0
	v_mov_b32_e32 v9, 0
	v_mov_b32_e32 v8, 0
	v_mov_b32_e32 v7, 0
	v_mov_b32_e32 v6, 0
	v_mov_b32_e32 v5, 0
	v_mov_b32_e32 v4, 0
	s_and_saveexec_b64 s[20:21], s[4:5]
	s_cbranch_execz .LBB0_982
	s_mov_b64 s[98:99], exec
	v_cmp_le_i32_e32 vcc, 3, v124
	s_and_b64 exec, exec, vcc
	s_cbranch_execz .Lselw_0
	v_add_u32_e32 v240, v118, v124
	v_mul_u32_u24_e32 v240, 0x4a00, v240
	v_or_b32_e32 v241, v134, v114
	v_lshl_add_u32 v240, v241, 1, v240
	v_add_u32_e32 v240, 0x1000, v240
	v_subrev_u32_e32 v241, 0x4a00, v240
	v_subrev_u32_e32 v242, 0x9400, v240
	v_subrev_u32_e32 v243, 0xde00, v240
	global_load_dword v244, v240, s[16:17]
	global_load_dword v245, v241, s[16:17]
	global_load_dword v246, v242, s[16:17]
	global_load_dword v247, v243, s[16:17]
.Lselw_0:
	s_mov_b64 exec, s[98:99]
	v_or_b32_e32 v128, v134, v114
	v_cmp_gt_i32_e32 vcc, 3, v124
	s_and_saveexec_b64 s[22:23], vcc
	s_xor_b64 s[22:23], exec, s[22:23]
	s_cbranch_execz .LBB0_961
	v_mov_b32_e32 v5, 0
	v_mov_b32_e32 v4, 0
	v_mov_b32_e32 v3, 0
	v_mov_b32_e32 v2, 0
	v_mov_b32_e32 v13, 0
	v_mov_b32_e32 v12, 0
	v_mov_b32_e32 v11, 0
	v_mov_b32_e32 v10, 0
	v_mov_b32_e32 v9, 0
	v_mov_b32_e32 v8, 0
	v_mov_b32_e32 v7, 0
	v_mov_b32_e32 v6, 0
	v_mov_b32_e32 v17, 0
	v_mov_b32_e32 v16, 0
	v_mov_b32_e32 v15, 0
	v_mov_b32_e32 v14, 0
	s_and_saveexec_b64 s[24:25], s[6:7]
	s_cbranch_execz .LBB0_960
	s_load_dwordx2 s[38:39], s[18:19], 0x40
	v_ashrrev_i32_e32 v125, 31, v124
	v_lshl_add_u64 v[2:3], v[120:121], 0, v[124:125]
	s_waitcnt lgkmcnt(0)
	v_mov_b64_e32 v[4:5], s[38:39]
	v_mad_u64_u32 v[4:5], s[38:39], v2, s69, v[4:5]
	v_mov_b32_e32 v2, v5
	v_mad_u64_u32 v[2:3], s[38:39], v3, s69, v[2:3]
	v_mov_b32_e32 v5, v2
	v_lshlrev_b32_e32 v2, 2, v128
	v_mov_b32_e32 v3, v0
	v_lshl_add_u64 v[2:3], v[4:5], 0, v[2:3]
	global_load_dwordx4 v[14:17], v[2:3], off
	global_load_dwordx4 v[6:9], v[2:3], off offset:16
	global_load_dwordx4 v[10:13], v[2:3], off offset:32
	s_nop 0
	global_load_dwordx4 v[2:5], v[2:3], off offset:48

; __device__ __forceinline__ void unpack8(u32x4 v, float* f) { f[0] = bflo(v[0]); f[1] = bfhi(v[0]); f[2] = bflo(v[1]); f[3] = bfhi(v[1]); f[4] = bflo(v[2]); f[5] = bfhi(v[2]); f[6] = bflo(v[3]); f[7] = bfhi(v[3]); }
; __device__ __forceinline__ u32x4 pack8(const float* f) { u32x4 r; r[0] = cvt_pk_bf16(f[0], f[1]); r[1] = cvt_pk_bf16(f[2], f[3]); r[2] = cvt_pk_bf16(f[4], f[5]); r[3] = cvt_pk_bf16(f[6], f[7]); return r; }
; __device__ __forceinline__ void dn_prep_unit(int layer, int sample, int b, int n, int h, unsigned char* shm) {
;     ...
;             if (tt < rows) {
; #pragma unroll
;                 for (int j = 0; j < 4; ++j) { const int lt = n * 64 + tt - 3 + j; float x[16];
;                     if (lt >= 0) { const bf16_t* s = P + (tokb + lt) * NINP + C_DQ + ch; unpack8(*(const u32x4*)s, x); unpack8(*(const u32x4*)(s + 8), x + 8); }
;     ...
;             if (sel < 2) { float ss = 0.f;
; #pragma unroll
;                 for (int i = 0; i < 16; ++i) ss += y[i] * y[i];
;                 ss += __shfl_xor(ss, 1); ss += __shfl_xor(ss, 2); ss += __shfl_xor(ss, 4);
;                 const float rs = rsqrtf(ss + 1e-6f);
; #pragma unroll
;                 for (int i = 0; i < 16; ++i) y[i] *= rs; }
;             if (sel == 0) { float t[16];
; #pragma unroll
;                 for (int i = 0; i < 16; ++i) t[i] = y[i] * 0.08838834764831845f;
;                 *(u32x4*)(Q16 + tt * 136 + part * 16) = pack8(t); *(u32x4*)(Q16 + tt * 136 + part * 16 + 8) = pack8(t + 8);
; #pragma unroll
;                 for (int i = 0; i < 16; ++i) t[i] *= eg;
;                 *(u32x4*)(QGg + tt * 128 + part * 16) = pack8(t); *(u32x4*)(QGg + tt * 128 + part * 16 + 8) = pack8(t + 8);
.LBB0_982:
	s_or_b64 exec, exec, s[20:21]
	v_mul_f32_e32 v28, v5, v5
	v_fmac_f32_e32 v28, v4, v4
	v_fmac_f32_e32 v28, v6, v6
	v_fmac_f32_e32 v28, v7, v7
	v_fmac_f32_e32 v28, v8, v8
	v_fmac_f32_e32 v28, v9, v9
	v_fmac_f32_e32 v28, v10, v10
	s_waitcnt lgkmcnt(1)
	v_mul_f32_e32 v2, 0x3fb8aa3b, v122
	v_fmac_f32_e32 v28, v11, v11
	v_pk_mul_f32 v[24:25], v[12:13], v[12:13]
	v_rndne_f32_e32 v3, v2
	s_mov_b32 s20, 0x3fb8aa3b
	v_add_f32_e32 v24, v24, v28
	v_sub_f32_e32 v20, v2, v3
	v_fma_f32 v2, v122, s20, -v2
	v_pk_mul_f32 v[22:23], v[14:15], v[14:15]
	v_add_f32_e32 v24, v25, v24
	v_fmac_f32_e32 v2, 0x32a5705f, v122
	v_add_f32_e32 v22, v22, v24
	v_add_f32_e32 v2, v20, v2
	v_pk_mul_f32 v[20:21], v[16:17], v[16:17]
	v_add_f32_e32 v22, v23, v22
	v_add_f32_e32 v20, v20, v22
	v_exp_f32_e32 v26, v2
	v_cvt_i32_f32_e32 v27, v3
	v_pk_mul_f32 v[2:3], v[18:19], v[18:19]
	v_add_f32_e32 v20, v21, v20
	v_add_f32_e32 v2, v2, v20
	v_and_b32_e32 v20, 64, v227
	v_add_f32_e32 v2, v3, v2
	v_xor_b32_e32 v3, 1, v227
	v_add_u32_e32 v20, 64, v20
	v_cmp_lt_i32_e32 vcc, v3, v20
	s_mov_b32 s20, 0xc2ce8ed0
	v_ldexp_f32 v22, v26, v27
	v_cndmask_b32_e32 v3, v227, v3, vcc
	v_lshlrev_b32_e32 v138, 2, v3
	ds_bpermute_b32 v21, v138, v2
	v_lshlrev_b32_e32 v130, 1, v134
	v_mov_b32_e32 v131, v0
	v_mul_lo_u32 v137, v135, s95
	v_mov_b32_e32 v3, 0
	s_waitcnt lgkmcnt(0)
	v_add_f32_e32 v2, v2, v21
	v_xor_b32_e32 v21, 2, v227
	v_cmp_lt_i32_e32 vcc, v21, v20
	s_nop 1
	v_cndmask_b32_e32 v21, v227, v21, vcc
	v_lshlrev_b32_e32 v139, 2, v21
	ds_bpermute_b32 v21, v139, v2
	v_cmp_ngt_f32_e32 vcc, s20, v122
	s_mov_b32 s20, 0x42b17218
	s_waitcnt lgkmcnt(0)
	v_add_f32_e32 v2, v2, v21
	v_cndmask_b32_e32 v22, 0, v22, vcc
	v_cmp_nlt_f32_e32 vcc, s20, v122
	v_xor_b32_e32 v21, 4, v227
	s_mov_b64 s[20:21], 0xc000
	v_cndmask_b32_e32 v128, v225, v22, vcc
	v_cmp_lt_i32_e32 vcc, v21, v20
	s_nop 1
	v_cndmask_b32_e32 v20, v227, v21, vcc
	v_lshlrev_b32_e32 v140, 2, v20
	ds_bpermute_b32 v22, v140, v2
	v_lshlrev_b32_e32 v20, 7, v135
	v_ashrrev_i32_e32 v21, 31, v20
	v_lshl_add_u64 v[132:133], v[20:21], 1, v[148:149]
	s_waitcnt lgkmcnt(0)
	v_add_f32_e32 v2, v2, v22
	v_add_f32_e32 v2, 0x358637bd, v2
	v_mul_f32_e32 v20, 0x4b800000, v2
	v_cmp_gt_f32_e32 vcc, s91, v2
	s_nop 1
	v_cndmask_b32_e32 v2, v2, v20, vcc
	v_rsq_f32_e32 v2, v2
	v_lshl_add_u64 v[20:21], v[132:133], 0, v[130:131]
	v_lshl_add_u64 v[22:23], v[20:21], 0, s[20:21]
	v_readlane_b32 s20, v254, 19
	v_mul_f32_e32 v24, 0x45800000, v2
	v_cndmask_b32_e32 v2, v2, v24, vcc
	v_mul_f32_e32 v11, v11, v2
	v_mul_f32_e32 v10, v10, v2
	v_mul_f32_e32 v9, v9, v2
	v_mul_f32_e32 v8, v8, v2
	v_mul_f32_e32 v7, v7, v2
	v_mul_f32_e32 v6, v6, v2
	v_mul_f32_e32 v5, v5, v2
	v_mul_f32_e32 v19, v19, v2
	v_mul_f32_e32 v18, v18, v2
	v_mul_f32_e32 v17, v17, v2
	v_mul_f32_e32 v16, v16, v2
	v_mul_f32_e32 v15, v15, v2
	v_mul_f32_e32 v14, v14, v2
	v_mul_f32_e32 v13, v13, v2
	v_mul_f32_e32 v12, v12, v2
	v_mul_f32_e32 v2, v4, v2
	v_mul_f32_e32 v24, 0x3db504f3, v5
	v_mul_f32_e32 v25, 0x3db504f3, v6
	v_mul_f32_e32 v26, 0x3db504f3, v7
	v_mul_f32_e32 v8, 0x3db504f3, v8
	v_mul_f32_e32 v9, 0x3db504f3, v9
	v_mul_f32_e32 v10, 0x3db504f3, v10
	v_mul_f32_e32 v11, 0x3db504f3, v11
	v_cvt_pk_bf16_f32 v5, v25, v26
	v_cvt_pk_bf16_f32 v6, v8, v9
	v_cvt_pk_bf16_f32 v7, v10, v11
	v_add3_u32 v27, s20, v130, v137
	v_mul_f32_e32 v2, 0x3db504f3, v2
	v_mul_f32_e32 v14, 0x3db504f3, v14
	v_mul_f32_e32 v15, 0x3db504f3, v15
	v_mul_f32_e32 v16, 0x3db504f3, v16
	v_mul_f32_e32 v17, 0x3db504f3, v17
	v_mul_f32_e32 v18, 0x3db504f3, v18
	v_mul_f32_e32 v19, 0x3db504f3, v19
	v_cvt_pk_bf16_f32 v4, v2, v24
	ds_write_b128 v27, v[4:7]
	v_cvt_pk_bf16_f32 v5, v14, v15
	v_cvt_pk_bf16_f32 v6, v16, v17
	v_cvt_pk_bf16_f32 v7, v18, v19
	v_mul_f32_e32 v12, 0x3db504f3, v12
	v_mul_f32_e32 v13, 0x3db504f3, v13
	v_cvt_pk_bf16_f32 v4, v12, v13
	ds_write_b128 v27, v[4:7] offset:16
	v_mul_f32_e32 v5, v128, v25
	v_mul_f32_e32 v6, v128, v26
	v_mul_f32_e32 v7, v128, v8
	v_mul_f32_e32 v8, v128, v9
	v_mul_f32_e32 v9, v128, v10
	v_cvt_pk_bf16_f32 v5, v5, v6
	v_cvt_pk_bf16_f32 v6, v7, v8
	v_add_co_u32_e32 v8, vcc, 0xc000, v20
	v_mul_f32_e32 v4, v128, v24
	v_mul_f32_e32 v10, v128, v11
	v_cvt_pk_bf16_f32 v7, v9, v10
	v_addc_co_u32_e32 v9, vcc, 0, v21, vcc
	v_mul_f32_e32 v2, v128, v2
	v_mul_f32_e32 v11, v128, v12
	v_mul_f32_e32 v12, v128, v13
	v_mul_f32_e32 v13, v128, v14
	v_mul_f32_e32 v14, v128, v15
	v_mul_f32_e32 v15, v128, v16
	v_mul_f32_e32 v16, v128, v17
	v_mul_f32_e32 v17, v128, v18
	v_mul_f32_e32 v18, v128, v19
	v_cvt_pk_bf16_f32 v4, v2, v4
	global_store_dwordx4 v[8:9], v[4:7], off
	v_mov_b32_e32 v2, 0
	v_mov_b32_e32 v9, 0
	v_cvt_pk_bf16_f32 v6, v15, v16
	v_cvt_pk_bf16_f32 v7, v17, v18
	v_cvt_pk_bf16_f32 v4, v11, v12
	v_cvt_pk_bf16_f32 v5, v13, v14
	global_store_dwordx4 v[22:23], v[4:7], off offset:16
	v_mov_b32_e32 v8, 0
	v_mov_b32_e32 v11, 0
	v_mov_b32_e32 v7, 0
	v_mov_b32_e32 v6, 0
	v_mov_b32_e32 v10, 0
	v_mov_b32_e32 v13, 0
	v_mov_b32_e32 v12, 0
	v_mov_b32_e32 v15, 0
	v_mov_b32_e32 v14, 0
	v_mov_b32_e32 v17, 0
	v_mov_b32_e32 v16, 0
	v_mov_b32_e32 v19, 0
	v_mov_b32_e32 v18, 0
	s_and_saveexec_b64 s[20:21], s[4:5]
	s_cbranch_execz .LBB0_1008
	s_mov_b64 s[98:99], exec
	v_cmp_le_i32_e32 vcc, 3, v124
	s_and_b64 exec, exec, vcc
	s_cbranch_execz .Lselw_1
	v_add_u32_e32 v240, v118, v124
	v_mul_u32_u24_e32 v240, 0x4a00, v240
	v_or_b32_e32 v241, v134, v114
	v_lshl_add_u32 v240, v241, 1, v240
	v_add_u32_e32 v240, 0x1800, v240
	v_subrev_u32_e32 v241, 0x4a00, v240
	v_subrev_u32_e32 v242, 0x9400, v240
	v_subrev_u32_e32 v243, 0xde00, v240
	global_load_dword v244, v240, s[16:17]
	global_load_dword v245, v241, s[16:17]
	global_load_dword v246, v242, s[16:17]
	global_load_dword v247, v243, s[16:17]
.Lselw_1:
	s_mov_b64 exec, s[98:99]
	v_or3_b32 v131, v134, v114, s71
	v_cmp_gt_i32_e32 vcc, 3, v124
	s_and_saveexec_b64 s[22:23], vcc
	s_xor_b64 s[22:23], exec, s[22:23]
	s_cbranch_execz .LBB0_987
	v_mov_b32_e32 v5, 0
	v_mov_b32_e32 v4, 0
	v_mov_b32_e32 v3, 0
	v_mov_b32_e32 v2, 0
	v_mov_b32_e32 v13, 0
	v_mov_b32_e32 v12, 0
	v_mov_b32_e32 v11, 0
	v_mov_b32_e32 v10, 0
	v_mov_b32_e32 v9, 0
	v_mov_b32_e32 v8, 0
	v_mov_b32_e32 v7, 0
	v_mov_b32_e32 v6, 0
	v_mov_b32_e32 v17, 0
	v_mov_b32_e32 v16, 0
	v_mov_b32_e32 v15, 0
	v_mov_b32_e32 v14, 0
	s_and_saveexec_b64 s[24:25], s[6:7]
	s_cbranch_execz .LBB0_986
	s_load_dwordx2 s[38:39], s[18:19], 0x40
	v_ashrrev_i32_e32 v125, 31, v124
	v_lshl_add_u64 v[2:3], v[120:121], 0, v[124:125]
	s_waitcnt lgkmcnt(0)
	v_mov_b64_e32 v[4:5], s[38:39]
	v_mad_u64_u32 v[4:5], s[38:39], v2, s69, v[4:5]
	v_mov_b32_e32 v2, v5
	v_mad_u64_u32 v[2:3], s[38:39], v3, s69, v[2:3]
	v_mov_b32_e32 v5, v2
	v_lshlrev_b32_e32 v2, 2, v131
	v_mov_b32_e32 v3, v0
	v_lshl_add_u64 v[2:3], v[4:5], 0, v[2:3]
	global_load_dwordx4 v[14:17], v[2:3], off
	global_load_dwordx4 v[6:9], v[2:3], off offset:16
	global_load_dwordx4 v[10:13], v[2:3], off offset:32
	s_nop 0
	global_load_dwordx4 v[2:5], v[2:3], off offset:48

; __device__ __forceinline__ void unpack8(u32x4 v, float* f) { f[0] = bflo(v[0]); f[1] = bfhi(v[0]); f[2] = bflo(v[1]); f[3] = bfhi(v[1]); f[4] = bflo(v[2]); f[5] = bfhi(v[2]); f[6] = bflo(v[3]); f[7] = bfhi(v[3]); }
; __device__ __forceinline__ u32x4 pack8(const float* f) { u32x4 r; r[0] = cvt_pk_bf16(f[0], f[1]); r[1] = cvt_pk_bf16(f[2], f[3]); r[2] = cvt_pk_bf16(f[4], f[5]); r[3] = cvt_pk_bf16(f[6], f[7]); return r; }
; __device__ __forceinline__ void dn_prep_unit(int layer, int sample, int b, int n, int h, unsigned char* shm) {
;     ...
;             if (tt < rows) {
; #pragma unroll
;                 for (int j = 0; j < 4; ++j) { const int lt = n * 64 + tt - 3 + j; float x[16];
;                     if (lt >= 0) { const bf16_t* s = P + (tokb + lt) * NINP + C_DQ + ch; unpack8(*(const u32x4*)s, x); unpack8(*(const u32x4*)(s + 8), x + 8); }
;     ...
;             } else if (sel == 1) { float t[16];
;                 *(u32x4*)(K16 + tt * 136 + part * 16) = pack8(y); *(u32x4*)(K16 + tt * 136 + part * 16 + 8) = pack8(y + 8);
; #pragma unroll
;                 for (int i = 0; i < 16; ++i) { RHS[tt * 260 + 128 + part * 16 + i] = y[i] * bt * eg; t[i] = y[i] * ekd; }
;                 *(u32x4*)(KDg + tt * 128 + part * 16) = pack8(t); *(u32x4*)(KDg + tt * 128 + part * 16 + 8) = pack8(t + 8);
.LBB0_1008:
	s_or_b64 exec, exec, s[20:21]
	v_mul_f32_e32 v30, v19, v19
	v_fmac_f32_e32 v30, v18, v18
	v_fmac_f32_e32 v30, v16, v16
	v_fmac_f32_e32 v30, v17, v17
	v_fmac_f32_e32 v30, v14, v14
	v_fmac_f32_e32 v30, v15, v15
	v_fmac_f32_e32 v30, v12, v12
	v_fmac_f32_e32 v30, v13, v13
	v_pk_mul_f32 v[24:25], v[10:11], v[10:11]
	v_pk_mul_f32 v[22:23], v[8:9], v[8:9]
	v_add_f32_e32 v24, v24, v30
	v_add_f32_e32 v24, v25, v24
	v_sub_f32_e32 v26, v136, v122
	v_add_f32_e32 v22, v22, v24
	v_mul_f32_e32 v4, 0x3fb8aa3b, v26
	v_pk_mul_f32 v[20:21], v[6:7], v[6:7]
	v_add_f32_e32 v22, v23, v22
	s_mov_b32 s20, 0x3fb8aa3b
	v_rndne_f32_e32 v28, v4
	v_add_f32_e32 v20, v20, v22
	v_fma_f32 v27, v26, s20, -v4
	v_sub_f32_e32 v29, v4, v28
	v_pk_mul_f32 v[4:5], v[2:3], v[2:3]
	v_add_f32_e32 v20, v21, v20
	v_add_f32_e32 v4, v4, v20
	v_add_f32_e32 v4, v5, v4
	ds_bpermute_b32 v5, v138, v4
	v_fmac_f32_e32 v27, 0x32a5705f, v26
	v_add_f32_e32 v20, v29, v27
	v_exp_f32_e32 v20, v20
	v_cvt_i32_f32_e32 v21, v28
	s_waitcnt lgkmcnt(0)
	v_add_f32_e32 v4, v4, v5
	ds_bpermute_b32 v22, v139, v4
	s_mov_b32 s20, 0xc2ce8ed0
	v_ldexp_f32 v20, v20, v21
	v_cmp_ngt_f32_e32 vcc, s20, v26
	s_mov_b32 s20, 0x42b17218
	s_waitcnt lgkmcnt(0)
	v_add_f32_e32 v4, v4, v22
	ds_bpermute_b32 v21, v140, v4
	v_cndmask_b32_e32 v20, 0, v20, vcc
	v_cmp_nlt_f32_e32 vcc, s20, v26
	v_mov_b32_e32 v5, 0
	v_mov_b32_e32 v131, v0
	s_waitcnt lgkmcnt(0)
	v_add_f32_e32 v4, v4, v21
	v_add_f32_e32 v4, 0x358637bd, v4
	v_cndmask_b32_e32 v31, v225, v20, vcc
	v_mul_f32_e32 v20, 0x4b800000, v4
	v_cmp_gt_f32_e32 vcc, s91, v4
	v_lshl_add_u64 v[26:27], v[132:133], 0, v[130:131]
	s_mov_b64 s[20:21], 0x10000
	v_cndmask_b32_e32 v4, v4, v20, vcc
	v_rsq_f32_e32 v4, v4
	v_mov_b32_e32 v30, v123
	v_lshl_add_u64 v[28:29], v[26:27], 0, s[20:21]
	v_readlane_b32 s20, v254, 20
	v_mul_f32_e32 v20, 0x45800000, v4
	v_cndmask_b32_e32 v4, v4, v20, vcc
	v_pk_mul_f32 v[20:21], v[18:19], v[4:5] op_sel_hi:[1,0]
	v_pk_mul_f32 v[16:17], v[16:17], v[4:5] op_sel_hi:[1,0]
	v_cvt_pk_bf16_f32 v18, v20, v21
	v_mul_f32_e32 v33, v31, v20
	v_pk_mul_f32 v[22:23], v[30:31], v[20:21] op_sel_hi:[0,1]
	v_mul_f32_e32 v34, v31, v21
	v_cvt_pk_bf16_f32 v19, v16, v17
	v_mul_f32_e32 v35, v31, v16
	v_pk_mul_f32 v[20:21], v[30:31], v[16:17] op_sel_hi:[0,1]
	v_mul_f32_e32 v36, v31, v17
	v_pk_mul_f32 v[16:17], v[14:15], v[4:5] op_sel_hi:[1,0]
	v_pk_mul_f32 v[12:13], v[12:13], v[4:5] op_sel_hi:[1,0]
	v_pk_mul_f32 v[24:25], v[128:129], v[20:21] op_sel_hi:[0,1]
	v_cvt_pk_bf16_f32 v20, v16, v17
	v_mul_f32_e32 v37, v31, v16
	v_pk_mul_f32 v[14:15], v[30:31], v[16:17] op_sel_hi:[0,1]
	v_mul_f32_e32 v38, v31, v17
	v_cvt_pk_bf16_f32 v21, v12, v13
	v_add3_u32 v39, s20, v130, v137
	v_mul_f32_e32 v40, v31, v12
	v_pk_mul_f32 v[16:17], v[30:31], v[12:13] op_sel_hi:[0,1]
	v_mul_f32_e32 v41, v31, v13
	v_pk_mul_f32 v[12:13], v[10:11], v[4:5] op_sel_hi:[1,0]
	v_pk_mul_f32 v[8:9], v[8:9], v[4:5] op_sel_hi:[1,0]
	ds_write_b128 v39, v[18:21]
	v_cvt_pk_bf16_f32 v10, v12, v13
	v_mul_f32_e32 v42, v31, v12
	v_pk_mul_f32 v[18:19], v[30:31], v[12:13] op_sel_hi:[0,1]
	v_mul_f32_e32 v43, v31, v13
	v_cvt_pk_bf16_f32 v11, v8, v9
	v_mul_f32_e32 v44, v31, v8
	v_pk_mul_f32 v[12:13], v[30:31], v[8:9] op_sel_hi:[0,1]
	v_mul_f32_e32 v45, v31, v9
	v_pk_mul_f32 v[8:9], v[6:7], v[4:5] op_sel_hi:[1,0]
	v_pk_mul_f32 v[2:3], v[2:3], v[4:5] op_sel_hi:[1,0]
	v_mul_lo_u32 v135, v135, s59
	v_lshlrev_b32_e32 v136, 2, v134
	v_pk_mul_f32 v[20:21], v[128:129], v[12:13] op_sel_hi:[0,1]
	v_cvt_pk_bf16_f32 v12, v8, v9
	v_mul_f32_e32 v46, v31, v8
	v_pk_mul_f32 v[6:7], v[30:31], v[8:9] op_sel_hi:[0,1]
	v_mul_f32_e32 v47, v31, v9
	v_pk_mul_f32 v[8:9], v[30:31], v[2:3] op_sel_hi:[0,1]
	s_mov_b32 s20, 0x10000
	v_add3_u32 v32, 0, v135, v136
	v_pk_mul_f32 v[6:7], v[128:129], v[6:7] op_sel_hi:[0,1]
	v_cvt_pk_bf16_f32 v13, v2, v3
	v_mul_f32_e32 v4, v31, v2
	v_pk_mul_f32 v[8:9], v[128:129], v[8:9] op_sel_hi:[0,1]
	v_add_co_u32_e32 v2, vcc, s20, v26
	v_pk_mul_f32 v[22:23], v[128:129], v[22:23] op_sel_hi:[0,1]
	v_pk_mul_f32 v[14:15], v[128:129], v[14:15] op_sel_hi:[0,1]
	v_pk_mul_f32 v[16:17], v[128:129], v[16:17] op_sel_hi:[0,1]
	v_pk_mul_f32 v[18:19], v[128:129], v[18:19] op_sel_hi:[0,1]
	ds_write_b128 v39, v[10:13] offset:16
	ds_write_b128 v32, v[22:25] offset:1024
	ds_write_b128 v32, v[14:17] offset:1040
	ds_write_b128 v32, v[18:21] offset:1056
	ds_write_b128 v32, v[6:9] offset:1072
	v_mul_f32_e32 v10, v31, v3
	v_cvt_pk_bf16_f32 v6, v33, v34
	v_cvt_pk_bf16_f32 v7, v35, v36
	v_cvt_pk_bf16_f32 v8, v37, v38
	v_cvt_pk_bf16_f32 v9, v40, v41
	v_addc_co_u32_e32 v3, vcc, 0, v27, vcc
	global_store_dwordx4 v[2:3], v[6:9], off
	v_mov_b32_e32 v3, 0
	v_mov_b32_e32 v2, 0
	v_cvt_pk_bf16_f32 v6, v42, v43
	v_cvt_pk_bf16_f32 v7, v44, v45
	v_cvt_pk_bf16_f32 v8, v46, v47
	v_cvt_pk_bf16_f32 v9, v4, v10
	global_store_dwordx4 v[28:29], v[6:9], off offset:16
	v_mov_b32_e32 v4, 0
	v_mov_b32_e32 v11, 0
	v_mov_b32_e32 v7, 0
	v_mov_b32_e32 v6, 0
	v_mov_b32_e32 v9, 0
	v_mov_b32_e32 v8, 0
	v_mov_b32_e32 v10, 0
	v_mov_b32_e32 v13, 0
	v_mov_b32_e32 v12, 0
	v_mov_b32_e32 v15, 0
	v_mov_b32_e32 v14, 0
	v_mov_b32_e32 v17, 0
	v_mov_b32_e32 v16, 0
	s_and_saveexec_b64 s[20:21], s[4:5]
	s_cbranch_execz .LBB0_1034
	s_mov_b64 s[98:99], exec
	v_cmp_le_i32_e32 vcc, 3, v124
	s_and_b64 exec, exec, vcc
	s_cbranch_execz .Lselw_2
	v_add_u32_e32 v240, v118, v124
	v_mul_u32_u24_e32 v240, 0x4a00, v240
	v_or_b32_e32 v241, v134, v114
	v_lshl_add_u32 v240, v241, 1, v240
	v_add_u32_e32 v240, 0x2000, v240
	v_subrev_u32_e32 v241, 0x4a00, v240
	v_subrev_u32_e32 v242, 0x9400, v240
	v_subrev_u32_e32 v243, 0xde00, v240
	global_load_dword v244, v240, s[16:17]
	global_load_dword v245, v241, s[16:17]
	global_load_dword v246, v242, s[16:17]
	global_load_dword v247, v243, s[16:17]
.Lselw_2:
	s_mov_b64 exec, s[98:99]
	v_or3_b32 v122, v134, v114, s72
	v_cmp_gt_i32_e32 vcc, 3, v124
	s_and_saveexec_b64 s[4:5], vcc
	s_xor_b64 s[4:5], exec, s[4:5]
	s_cbranch_execz .LBB0_1013
	v_mov_b32_e32 v5, 0
	v_mov_b32_e32 v4, 0
	v_mov_b32_e32 v3, 0
	v_mov_b32_e32 v2, 0
	v_mov_b32_e32 v13, 0
	v_mov_b32_e32 v12, 0
	v_mov_b32_e32 v11, 0
	v_mov_b32_e32 v10, 0
	v_mov_b32_e32 v9, 0
	v_mov_b32_e32 v8, 0
	v_mov_b32_e32 v7, 0
	v_mov_b32_e32 v6, 0
	v_mov_b32_e32 v17, 0
	v_mov_b32_e32 v16, 0
	v_mov_b32_e32 v15, 0
	v_mov_b32_e32 v14, 0
	s_and_saveexec_b64 s[22:23], s[6:7]
	s_cbranch_execz .LBB0_1012
	s_load_dwordx2 s[24:25], s[18:19], 0x40
	v_ashrrev_i32_e32 v125, 31, v124
	v_lshl_add_u64 v[2:3], v[120:121], 0, v[124:125]
	s_waitcnt lgkmcnt(0)
	v_mov_b64_e32 v[4:5], s[24:25]
	v_mad_u64_u32 v[4:5], s[24:25], v2, s69, v[4:5]
	v_mov_b32_e32 v2, v5
	v_mad_u64_u32 v[2:3], s[24:25], v3, s69, v[2:3]
	v_mov_b32_e32 v5, v2
	v_lshlrev_b32_e32 v2, 2, v122
	v_mov_b32_e32 v3, v0
	v_lshl_add_u64 v[2:3], v[4:5], 0, v[2:3]
	global_load_dwordx4 v[14:17], v[2:3], off
	global_load_dwordx4 v[6:9], v[2:3], off offset:16
	global_load_dwordx4 v[10:13], v[2:3], off offset:32
	s_nop 0
	global_load_dwordx4 v[2:5], v[2:3], off offset:48
